# speedup vs baseline: 1.0105x; 1.0021x over previous
; #define PG8_STAGE(bufoff, gbase, voff) do { _Pragma("unroll") for (int _i = 0; _i < 2; ++_i) \
;         __builtin_amdgcn_global_load_lds((const unsigned*)((const char*)(gbase) + (voff)[_i]), (PG8_LAS unsigned*)(lds + (bufoff) + ldsw + _i * 8192), 16, 0, 0); } while (0)
; #define PG8_LDA(dst, b, h) do { _Pragma("unroll") for (int m = 0; m < 4; ++m) _Pragma("unroll") for (int k = 0; k < 2; ++k) dst[m][k] = *(const PG8_LAS bf16x8*)(lds + PG8_SA(b, h) + aoff + m * 2048 + k * 1024); } while (0)
; #define PG8_LDB(dst, b, h) do { _Pragma("unroll") for (int n = 0; n < 2; ++n) _Pragma("unroll") for (int k = 0; k < 2; ++k) dst[n][k] = *(const PG8_LAS bf16x8*)(lds + PG8_SB(b, h) + boff + n * 2048 + k * 1024); } while (0)
; #define PG8_SCHED __builtin_amdgcn_sched_barrier(0)
;     __device__ __forceinline__ bool next(int i, Unit& u) const {
;         const int L = i * so.G + so.c;
;         int pm, pn, kt0 = 0, nkt = nt, part = -1; bool ok = true;
;         if (L < full) {
;             int wgid = L; { const int q = so.nwg / NXCD, r = so.nwg % NXCD, xcd = wgid % NXCD, off = wgid / NXCD; wgid = (xcd < r ? xcd * (q + 1) : r * (q + 1) + (xcd - r) * q) + off; }
;             const int nig = wgm * so.nN, gid = wgid / nig, fm = gid * wgm, gsz = (so.nM - fm) < wgm ? (so.nM - fm) : wgm;
;             pm = fm + ((wgid % nig) % gsz); pn = (wgid % nig) / gsz;
;         } else {
;             const int T = L - full; ok = T < ntail;
;             const int npt = ntail / (nN * ts), y = T / npt; pm = pm0 + T % npt; pn = y % nN; part = y / nN; nkt = nt / ts; kt0 = part * nkt;
;         }
;         u.pm = pm; u.pn = pn; u.kt0 = kt0; u.nkt = nkt; u.part = part; return ok;
;     }
; template <class Epi, class Sched, bool ALIGN_EPI = false, bool SP2 = false>
; __device__ __forceinline__ void gemm_phase(PG8_LAS unsigned char* lds, const Gemm g, const Sched& S, const Epi& E) {
;     ...
;             PG8_LDB(B0, 0, 0); PG8_LDB(B1, 0, 1); PG8_SCHED; PG8_LDA(At, 0, 0); PG8_STAGE(PG8_SA(1, 1), a1 + hstep, voffA);
.LBB0_346:
	ds_read_b128 v[148:151], v242
	ds_read_b128 v[152:155], v242 offset:1024
	ds_read_b128 v[156:159], v242 offset:2048
	ds_read_b128 v[160:163], v242 offset:3072
	ds_read_b128 v[164:167], v242 offset:16384
	ds_read_b128 v[168:171], v242 offset:17408
	ds_read_b128 v[172:175], v242 offset:18432
	ds_read_b128 v[176:179], v242 offset:19456
	ds_read_b128 v[182:185], v147
	ds_read_b128 v[186:189], v147 offset:1024
	ds_read_b128 v[208:211], v147 offset:2048
	ds_read_b128 v[212:215], v147 offset:3072
	ds_read_b128 v[216:219], v147 offset:4096
	ds_read_b128 v[220:223], v147 offset:5120
	ds_read_b128 v[224:227], v147 offset:6144
	ds_read_b128 v[228:231], v147 offset:7168
	s_add_i32 s17, s18, 1
	s_mul_i32 s33, s17, s3
	s_add_i32 s33, s33, s2
	s_cmp_ge_i32 s33, s52
	s_mov_b64 s[34:35], -1
	s_cbranch_scc0 .LBB0_348
	s_sub_i32 s4, s33, s52
	s_mul_hi_u32 s12, s4, s77
	s_cmp_lt_i32 s4, s53
	s_mul_i32 s19, s12, s76
	s_cselect_b64 s[36:37], -1, 0
	s_sub_i32 s19, s4, s19
	s_add_i32 s34, s12, 1
	s_sub_i32 s35, s19, s76
	s_cmp_ge_u32 s19, s76
	s_cselect_b32 s12, s34, s12
	s_cselect_b32 s19, s35, s19
	s_add_i32 s34, s12, 1
	s_cmp_ge_u32 s19, s76
	s_cselect_b32 s19, s34, s12
	s_mul_i32 s12, s19, s76
	s_sub_i32 s4, s4, s12
	s_add_i32 s65, s4, 64
	s_mul_hi_u32 s4, s19, s69
	s_mul_i32 s12, s4, s7
	s_sub_i32 s12, s19, s12
	s_add_i32 s34, s4, 1
	s_sub_i32 s35, s12, s7
	s_cmp_ge_u32 s12, s7
	s_cselect_b32 s4, s34, s4
	s_cselect_b32 s12, s35, s12
	s_add_i32 s34, s4, 1
	s_cmp_ge_u32 s12, s7
	s_cselect_b32 s12, s34, s4
	s_mul_i32 s4, s12, s7
	s_sub_i32 s4, s19, s4
	s_mul_i32 s19, s12, s91
	s_mov_b64 s[34:35], 0

; #define PG8_STAGE(bufoff, gbase, voff) do { _Pragma("unroll") for (int _i = 0; _i < 2; ++_i) \
;         __builtin_amdgcn_global_load_lds((const unsigned*)((const char*)(gbase) + (voff)[_i]), (PG8_LAS unsigned*)(lds + (bufoff) + ldsw + _i * 8192), 16, 0, 0); } while (0)
; #define PG8_LDA(dst, b, h) do { _Pragma("unroll") for (int m = 0; m < 4; ++m) _Pragma("unroll") for (int k = 0; k < 2; ++k) dst[m][k] = *(const PG8_LAS bf16x8*)(lds + PG8_SA(b, h) + aoff + m * 2048 + k * 1024); } while (0)
; #define PG8_LDB(dst, b, h) do { _Pragma("unroll") for (int n = 0; n < 2; ++n) _Pragma("unroll") for (int k = 0; k < 2; ++k) dst[n][k] = *(const PG8_LAS bf16x8*)(lds + PG8_SB(b, h) + boff + n * 2048 + k * 1024); } while (0)
; #define PG8_MMA(ai, bj, At, Bt) do { __builtin_amdgcn_s_setprio(1); _Pragma("unroll") for (int m = 0; m < 4; ++m) _Pragma("unroll") for (int n = 0; n < 2; ++n) _Pragma("unroll") for (int k = 0; k < 2; ++k) \
;         acc[ai][bj][m][n] = __builtin_amdgcn_mfma_f32_16x16x32_bf16(Bt[n][k], At[m][k], acc[ai][bj][m][n], 0, 0, 0); __builtin_amdgcn_s_setprio(0); } while (0)
; #define PG8_WAIT_V(n) asm volatile("s_waitcnt vmcnt(" #n ")" ::: "memory")
; #define PG8_WAIT_L(n) asm volatile("s_waitcnt lgkmcnt(" #n ")" ::: "memory")
; #define PG8_BAR __builtin_amdgcn_s_barrier()
; #define PG8_SCHED __builtin_amdgcn_sched_barrier(0)
; template <class Epi, class Sched, bool ALIGN_EPI = false, bool SP2 = false>
; __device__ __forceinline__ void gemm_phase(PG8_LAS unsigned char* lds, const Gemm g, const Sched& S, const Epi& E) {
;     ...
;             PG8_LDB(B0, 0, 0); PG8_LDB(B1, 0, 1); PG8_SCHED; PG8_LDA(At, 0, 0); PG8_STAGE(PG8_SA(1, 1), a1 + hstep, voffA);
;             PG8_WAIT_V(8); PG8_WAIT_L(0); PG8_BAR; PG8_MMA(0, 0, At, B0); PG8_MMA(0, 1, At, B1); PG8_BAR; PG8_SCHED;
;             PG8_LDA(At, 0, 1); PG8_STAGE(PG8_SB(0, 0), b2, voffB); PG8_STAGE(PG8_SB(0, 1), b2 + hstep, voffB); PG8_STAGE(PG8_SA(0, 0), a2, voffA);
;             PG8_WAIT_V(8); PG8_WAIT_L(0); PG8_BAR; PG8_MMA(1, 0, At, B0); PG8_MMA(1, 1, At, B1); PG8_BAR; PG8_SCHED;
.LBB0_355:
	s_add_i32 s80, s80, 2
	s_add_u32 s82, s62, s60
	s_addc_u32 s83, s63, s61
	v_lshl_add_u64 v[232:233], v[140:141], 0, s[50:51]
	s_add_i32 m0, s98, 0xc000
	global_load_lds_dwordx4 v[232:233], off
	v_lshl_add_u64 v[232:233], v[142:143], 0, s[50:51]
	s_add_i32 m0, s98, 0xe000
	s_nop 0
	global_load_lds_dwordx4 v[232:233], off
	s_setprio 1
	s_waitcnt vmcnt(8) lgkmcnt(0)
	s_barrier
	v_mfma_f32_16x16x32_bf16 v[126:129], v[148:151], v[182:185], 0
	v_mfma_f32_16x16x32_bf16 v[122:125], v[156:159], v[182:185], 0
	v_mfma_f32_16x16x32_bf16 v[118:121], v[148:151], v[208:211], 0
	v_mfma_f32_16x16x32_bf16 v[110:113], v[156:159], v[208:211], 0
	v_mfma_f32_16x16x32_bf16 v[102:105], v[148:151], v[216:219], 0
	v_mfma_f32_16x16x32_bf16 v[94:97], v[156:159], v[216:219], 0
	v_mfma_f32_16x16x32_bf16 v[86:89], v[148:151], v[224:227], 0
	v_mfma_f32_16x16x32_bf16 v[78:81], v[156:159], v[224:227], 0
	v_mfma_f32_16x16x32_bf16 v[126:129], v[152:155], v[186:189], v[126:129]
	v_mfma_f32_16x16x32_bf16 v[122:125], v[160:163], v[186:189], v[122:125]
	v_mfma_f32_16x16x32_bf16 v[118:121], v[152:155], v[212:215], v[118:121]
	v_mfma_f32_16x16x32_bf16 v[110:113], v[160:163], v[212:215], v[110:113]
	v_mfma_f32_16x16x32_bf16 v[102:105], v[152:155], v[220:223], v[102:105]
	v_mfma_f32_16x16x32_bf16 v[94:97], v[160:163], v[220:223], v[94:97]
	v_mfma_f32_16x16x32_bf16 v[86:89], v[152:155], v[228:231], v[86:89]
	v_mfma_f32_16x16x32_bf16 v[78:81], v[160:163], v[228:231], v[78:81]
	v_mfma_f32_16x16x32_bf16 v[114:117], v[164:167], v[182:185], 0
	v_mfma_f32_16x16x32_bf16 v[106:109], v[172:175], v[182:185], 0
	v_mfma_f32_16x16x32_bf16 v[98:101], v[164:167], v[208:211], 0
	v_mfma_f32_16x16x32_bf16 v[90:93], v[172:175], v[208:211], 0
	v_mfma_f32_16x16x32_bf16 v[82:85], v[164:167], v[216:219], 0
	v_mfma_f32_16x16x32_bf16 v[74:77], v[172:175], v[216:219], 0
	v_mfma_f32_16x16x32_bf16 v[70:73], v[164:167], v[224:227], 0
	v_mfma_f32_16x16x32_bf16 v[66:69], v[172:175], v[224:227], 0
	v_mfma_f32_16x16x32_bf16 v[114:117], v[168:171], v[186:189], v[114:117]
	v_mfma_f32_16x16x32_bf16 v[106:109], v[176:179], v[186:189], v[106:109]
	v_mfma_f32_16x16x32_bf16 v[98:101], v[168:171], v[212:215], v[98:101]
	v_mfma_f32_16x16x32_bf16 v[90:93], v[176:179], v[212:215], v[90:93]
	v_mfma_f32_16x16x32_bf16 v[82:85], v[168:171], v[220:223], v[82:85]
	v_mfma_f32_16x16x32_bf16 v[74:77], v[176:179], v[220:223], v[74:77]
	v_mfma_f32_16x16x32_bf16 v[70:73], v[168:171], v[228:231], v[70:73]
	v_mfma_f32_16x16x32_bf16 v[66:69], v[176:179], v[228:231], v[66:69]
	s_setprio 0
	s_barrier
	s_add_i32 m0, s97, 0x10000
	ds_read_b128 v[182:185], v147 offset:16384
	ds_read_b128 v[186:189], v147 offset:17408
	ds_read_b128 v[208:211], v147 offset:18432
	ds_read_b128 v[212:215], v147 offset:19456
	ds_read_b128 v[216:219], v147 offset:20480
	ds_read_b128 v[220:223], v147 offset:21504
	ds_read_b128 v[224:227], v147 offset:22528
	ds_read_b128 v[228:231], v147 offset:23552
	global_load_lds_dwordx4 v0, s[56:57]
	s_add_i32 m0, s97, 0x12000
	s_add_u32 s38, s56, s16
	s_addc_u32 s39, s57, 0
	global_load_lds_dwordx4 v134, s[56:57]
	s_add_i32 m0, s97, 0x14000
	s_nop 0
	global_load_lds_dwordx4 v0, s[38:39]
	s_add_i32 m0, s97, 0x16000
	s_nop 0
	global_load_lds_dwordx4 v134, s[38:39]
	s_mov_b32 m0, s98
	s_nop 0
	global_load_lds_dwordx4 v130, s[62:63]
	s_mov_b32 m0, s99
	s_nop 0
	global_load_lds_dwordx4 v132, s[62:63]
	s_setprio 1
	s_waitcnt vmcnt(8) lgkmcnt(0)
	s_barrier
	v_mfma_f32_16x16x32_bf16 v[62:65], v[148:151], v[182:185], 0
	v_mfma_f32_16x16x32_bf16 v[58:61], v[156:159], v[182:185], 0
	v_mfma_f32_16x16x32_bf16 v[54:57], v[148:151], v[208:211], 0
	v_mfma_f32_16x16x32_bf16 v[46:49], v[156:159], v[208:211], 0
	v_mfma_f32_16x16x32_bf16 v[38:41], v[148:151], v[216:219], 0
	v_mfma_f32_16x16x32_bf16 v[30:33], v[156:159], v[216:219], 0
	v_mfma_f32_16x16x32_bf16 v[22:25], v[148:151], v[224:227], 0
	v_mfma_f32_16x16x32_bf16 v[14:17], v[156:159], v[224:227], 0
	v_mfma_f32_16x16x32_bf16 v[62:65], v[152:155], v[186:189], v[62:65]
	v_mfma_f32_16x16x32_bf16 v[58:61], v[160:163], v[186:189], v[58:61]
	v_mfma_f32_16x16x32_bf16 v[54:57], v[152:155], v[212:215], v[54:57]
	v_mfma_f32_16x16x32_bf16 v[46:49], v[160:163], v[212:215], v[46:49]
	v_mfma_f32_16x16x32_bf16 v[38:41], v[152:155], v[220:223], v[38:41]
	v_mfma_f32_16x16x32_bf16 v[30:33], v[160:163], v[220:223], v[30:33]
	v_mfma_f32_16x16x32_bf16 v[22:25], v[152:155], v[228:231], v[22:25]
	v_mfma_f32_16x16x32_bf16 v[14:17], v[160:163], v[228:231], v[14:17]
	v_mfma_f32_16x16x32_bf16 v[50:53], v[164:167], v[182:185], 0
	v_mfma_f32_16x16x32_bf16 v[42:45], v[172:175], v[182:185], 0
	v_mfma_f32_16x16x32_bf16 v[34:37], v[164:167], v[208:211], 0
	v_mfma_f32_16x16x32_bf16 v[26:29], v[172:175], v[208:211], 0
	v_mfma_f32_16x16x32_bf16 v[18:21], v[164:167], v[216:219], 0
	v_mfma_f32_16x16x32_bf16 v[10:13], v[172:175], v[216:219], 0
	v_mfma_f32_16x16x32_bf16 v[6:9], v[164:167], v[224:227], 0
	v_mfma_f32_16x16x32_bf16 v[2:5], v[172:175], v[224:227], 0
	v_mfma_f32_16x16x32_bf16 v[50:53], v[168:171], v[186:189], v[50:53]
	v_mfma_f32_16x16x32_bf16 v[42:45], v[176:179], v[186:189], v[42:45]
	v_mfma_f32_16x16x32_bf16 v[34:37], v[168:171], v[212:215], v[34:37]
	v_mfma_f32_16x16x32_bf16 v[26:29], v[176:179], v[212:215], v[26:29]
	v_mfma_f32_16x16x32_bf16 v[18:21], v[168:171], v[220:223], v[18:21]
	v_mfma_f32_16x16x32_bf16 v[10:13], v[176:179], v[220:223], v[10:13]
	v_mfma_f32_16x16x32_bf16 v[6:9], v[168:171], v[228:231], v[6:9]
	v_mfma_f32_16x16x32_bf16 v[2:5], v[176:179], v[228:231], v[2:5]
	s_setprio 0
	s_barrier
; #define PG8_STAGE(bufoff, gbase, voff) do { _Pragma("unroll") for (int _i = 0; _i < 2; ++_i) \
;         __builtin_amdgcn_global_load_lds((const unsigned*)((const char*)(gbase) + (voff)[_i]), (PG8_LAS unsigned*)(lds + (bufoff) + ldsw + _i * 8192), 16, 0, 0); } while (0)
; #define PG8_LDA(dst, b, h) do { _Pragma("unroll") for (int m = 0; m < 4; ++m) _Pragma("unroll") for (int k = 0; k < 2; ++k) dst[m][k] = *(const PG8_LAS bf16x8*)(lds + PG8_SA(b, h) + aoff + m * 2048 + k * 1024); } while (0)
; #define PG8_LDB(dst, b, h) do { _Pragma("unroll") for (int n = 0; n < 2; ++n) _Pragma("unroll") for (int k = 0; k < 2; ++k) dst[n][k] = *(const PG8_LAS bf16x8*)(lds + PG8_SB(b, h) + boff + n * 2048 + k * 1024); } while (0)
; #define PG8_MMA(ai, bj, At, Bt) do { __builtin_amdgcn_s_setprio(1); _Pragma("unroll") for (int m = 0; m < 4; ++m) _Pragma("unroll") for (int n = 0; n < 2; ++n) _Pragma("unroll") for (int k = 0; k < 2; ++k) \
;         acc[ai][bj][m][n] = __builtin_amdgcn_mfma_f32_16x16x32_bf16(Bt[n][k], At[m][k], acc[ai][bj][m][n], 0, 0, 0); __builtin_amdgcn_s_setprio(0); } while (0)
; #define PG8_WAIT_V(n) asm volatile("s_waitcnt vmcnt(" #n ")" ::: "memory")
; #define PG8_WAIT_L(n) asm volatile("s_waitcnt lgkmcnt(" #n ")" ::: "memory")
; #define PG8_BAR __builtin_amdgcn_s_barrier()
; #define PG8_SCHED __builtin_amdgcn_sched_barrier(0)
; template <class Epi, class Sched, bool ALIGN_EPI = false, bool SP2 = false>
; __device__ __forceinline__ void gemm_phase(PG8_LAS unsigned char* lds, const Gemm g, const Sched& S, const Epi& E) {
;     ...
;             PG8_LDB(B0, 1, 0); PG8_LDB(B1, 1, 1); PG8_SCHED; PG8_LDA(At, 1, 0); PG8_STAGE(PG8_SA(0, 1), a2 + hstep, voffA);
;             PG8_WAIT_V(8); PG8_WAIT_L(0); PG8_BAR; PG8_MMA(0, 0, At, B0); PG8_MMA(0, 1, At, B1); PG8_BAR; PG8_SCHED;
;             PG8_LDA(At, 1, 1); PG8_STAGE(PG8_SB(1, 0), b3, voffB); PG8_STAGE(PG8_SB(1, 1), b3 + hstep, voffB); PG8_STAGE(PG8_SA(1, 0), a3, voffA);
;             PG8_WAIT_V(8); PG8_WAIT_L(0); PG8_BAR; PG8_MMA(1, 0, At, B0); PG8_MMA(1, 1, At, B1); PG8_BAR; PG8_SCHED;
	ds_read_b128 v[148:151], v242 offset:32768
	ds_read_b128 v[152:155], v242 offset:33792
	ds_read_b128 v[156:159], v242 offset:34816
	ds_read_b128 v[160:163], v242 offset:35840
	ds_read_b128 v[164:167], v242 offset:49152
	ds_read_b128 v[168:171], v242 offset:50176
	ds_read_b128 v[172:175], v242 offset:51200
	ds_read_b128 v[176:179], v242 offset:52224
	s_add_u32 s38, s62, s16
	s_addc_u32 s39, s63, 0
	s_mov_b32 m0, s68
	ds_read_b128 v[182:185], v147 offset:32768
	ds_read_b128 v[186:189], v147 offset:33792
	ds_read_b128 v[208:211], v147 offset:34816
	ds_read_b128 v[212:215], v147 offset:35840
	ds_read_b128 v[216:219], v147 offset:36864
	ds_read_b128 v[220:223], v147 offset:37888
	ds_read_b128 v[224:227], v147 offset:38912
	ds_read_b128 v[228:231], v147 offset:39936
	global_load_lds_dwordx4 v130, s[38:39]
	s_mov_b32 m0, s64
	s_nop 0
	global_load_lds_dwordx4 v132, s[38:39]
	s_setprio 1
	s_waitcnt vmcnt(8) lgkmcnt(0)
	s_barrier
	v_mfma_f32_16x16x32_bf16 v[126:129], v[148:151], v[182:185], v[126:129]
	v_mfma_f32_16x16x32_bf16 v[122:125], v[156:159], v[182:185], v[122:125]
	v_mfma_f32_16x16x32_bf16 v[118:121], v[148:151], v[208:211], v[118:121]
	v_mfma_f32_16x16x32_bf16 v[110:113], v[156:159], v[208:211], v[110:113]
	v_mfma_f32_16x16x32_bf16 v[102:105], v[148:151], v[216:219], v[102:105]
	v_mfma_f32_16x16x32_bf16 v[94:97], v[156:159], v[216:219], v[94:97]
	v_mfma_f32_16x16x32_bf16 v[86:89], v[148:151], v[224:227], v[86:89]
	v_mfma_f32_16x16x32_bf16 v[78:81], v[156:159], v[224:227], v[78:81]
	v_mfma_f32_16x16x32_bf16 v[126:129], v[152:155], v[186:189], v[126:129]
	v_mfma_f32_16x16x32_bf16 v[122:125], v[160:163], v[186:189], v[122:125]
	v_mfma_f32_16x16x32_bf16 v[118:121], v[152:155], v[212:215], v[118:121]
	v_mfma_f32_16x16x32_bf16 v[110:113], v[160:163], v[212:215], v[110:113]
	v_mfma_f32_16x16x32_bf16 v[102:105], v[152:155], v[220:223], v[102:105]
	v_mfma_f32_16x16x32_bf16 v[94:97], v[160:163], v[220:223], v[94:97]
	v_mfma_f32_16x16x32_bf16 v[86:89], v[152:155], v[228:231], v[86:89]
	v_mfma_f32_16x16x32_bf16 v[78:81], v[160:163], v[228:231], v[78:81]
	v_mfma_f32_16x16x32_bf16 v[114:117], v[164:167], v[182:185], v[114:117]
	v_mfma_f32_16x16x32_bf16 v[106:109], v[172:175], v[182:185], v[106:109]
	v_mfma_f32_16x16x32_bf16 v[98:101], v[164:167], v[208:211], v[98:101]
	v_mfma_f32_16x16x32_bf16 v[90:93], v[172:175], v[208:211], v[90:93]
	v_mfma_f32_16x16x32_bf16 v[82:85], v[164:167], v[216:219], v[82:85]
	v_mfma_f32_16x16x32_bf16 v[74:77], v[172:175], v[216:219], v[74:77]
	v_mfma_f32_16x16x32_bf16 v[70:73], v[164:167], v[224:227], v[70:73]
	v_mfma_f32_16x16x32_bf16 v[66:69], v[172:175], v[224:227], v[66:69]
	v_mfma_f32_16x16x32_bf16 v[114:117], v[168:171], v[186:189], v[114:117]
	v_mfma_f32_16x16x32_bf16 v[106:109], v[176:179], v[186:189], v[106:109]
	v_mfma_f32_16x16x32_bf16 v[98:101], v[168:171], v[212:215], v[98:101]
	v_mfma_f32_16x16x32_bf16 v[90:93], v[176:179], v[212:215], v[90:93]
	v_mfma_f32_16x16x32_bf16 v[82:85], v[168:171], v[220:223], v[82:85]
	v_mfma_f32_16x16x32_bf16 v[74:77], v[176:179], v[220:223], v[74:77]
	v_mfma_f32_16x16x32_bf16 v[70:73], v[168:171], v[228:231], v[70:73]
	v_mfma_f32_16x16x32_bf16 v[66:69], v[176:179], v[228:231], v[66:69]
	s_setprio 0
	s_barrier
	s_add_u32 s38, s56, s60
	s_addc_u32 s39, s57, s61
	s_add_i32 m0, s97, 0x18000
	ds_read_b128 v[182:185], v147 offset:49152
	ds_read_b128 v[186:189], v147 offset:50176
	ds_read_b128 v[208:211], v147 offset:51200
	ds_read_b128 v[212:215], v147 offset:52224
	ds_read_b128 v[216:219], v147 offset:53248
	ds_read_b128 v[220:223], v147 offset:54272
	ds_read_b128 v[224:227], v147 offset:55296
	ds_read_b128 v[228:231], v147 offset:56320
	global_load_lds_dwordx4 v0, s[38:39]
	s_add_i32 m0, s97, 0x1a000
	s_nop 0
	global_load_lds_dwordx4 v134, s[38:39]
	s_add_u32 s38, s38, s16
	s_addc_u32 s39, s39, 0
	s_add_i32 m0, s97, 0x1c000
	global_load_lds_dwordx4 v0, s[38:39]
	s_add_i32 m0, s97, 0x1e000
	s_nop 0
	global_load_lds_dwordx4 v134, s[38:39]
	s_mov_b32 m0, s72
	s_nop 0
	global_load_lds_dwordx4 v130, s[82:83]
	s_mov_b32 m0, s73
	s_nop 0
	global_load_lds_dwordx4 v132, s[82:83]
	s_add_u32 s50, s50, s48
	s_addc_u32 s51, s51, s49
	s_cmp_ge_u32 s80, s13
	s_cselect_b64 vcc, -1, 0
	s_cbranch_scc1 .Lgemm_ctl_done_p
	s_cmp_eq_u32 s88, s80
	s_cbranch_scc1 .Lgemm_ctl_last_p
	s_add_u32 s62, s18, s50
	s_addc_u32 s63, s19, s51
	s_add_u32 s56, s87, s50
	s_addc_u32 s57, s33, s51
	s_mov_b64 s[60:61], s[44:45]
	s_branch .Lgemm_ctl_join_p
